# seam flag prefetch: leader thread loads the conversion-done counter before the arrive drain at the 4 flag seams, original load replaced by the prefetched value (poll loop unchanged)
# baseline (speedup 1.0000x reference)
.LBB0_349:
	v_readlane_b32 s98, v253, 30
	v_readlane_b32 s99, v253, 31
	s_mov_b64 s[100:101], exec
	s_and_b64 exec, exec, s[98:99]
	s_cbranch_execz .Lfp1_skip
	v_mov_b32_e32 v254, 0
	global_load_dword v254, v254, s[96:97] offset:768 sc1
.Lfp1_skip:
	s_mov_b64 exec, s[100:101]
	s_waitcnt vmcnt(0)
	s_add_i32 s15, s34, 0xffffff80
	s_waitcnt vmcnt(0)
	s_barrier
	s_mov_b64 s[4:5], exec
	v_readlane_b32 s6, v253, 30
	v_readlane_b32 s7, v253, 31
	s_and_b64 s[6:7], s[4:5], s[6:7]
	s_mov_b64 exec, s[6:7]
	s_cbranch_execz .LBB0_383
	s_lshl_b32 s8, s58, 6
	s_ashr_i32 s9, s8, 31
	s_lshl_b64 s[8:9], s[8:9], 2
	s_mov_b64 s[6:7], exec
	s_add_u32 s8, s96, s8
	s_addc_u32 s9, s97, s9
	v_mbcnt_lo_u32_b32 v1, s6, 0
	s_add_u32 s10, s8, 0x14000
	v_mbcnt_hi_u32_b32 v1, s7, v1
	s_addc_u32 s11, s9, 0
	v_cmp_eq_u32_e32 vcc, 0, v1
	s_and_saveexec_b64 s[8:9], vcc
	s_cbranch_execz .LBB0_352
	s_bcnt1_i32_b64 s6, s[6:7]
	v_mov_b32_e32 v2, 0
	v_mov_b32_e32 v3, s6
	global_atomic_add v2, v2, v3, s[10:11] sc0

.LBB0_367:
	s_or_b64 exec, exec, s[8:9]
	v_mov_b32_e32 v1, v254
	s_waitcnt vmcnt(0)
	v_cmp_le_u32_e32 vcc, s15, v1
	s_cbranch_vccnz .LBB0_382
	v_add_u32_e32 v1, 1, v2
	s_mov_b64 s[8:9], 0
	v_mov_b32_e32 v2, 0
	s_branch .LBB0_370

.LBB0_834:
	v_readlane_b32 s98, v253, 30
	v_readlane_b32 s99, v253, 31
	s_mov_b64 s[100:101], exec
	s_and_b64 exec, exec, s[98:99]
	s_cbranch_execz .Lfp2_skip
	v_mov_b32_e32 v254, 0
	global_load_dword v254, v254, s[96:97] offset:1024 sc1
.Lfp2_skip:
	s_mov_b64 exec, s[100:101]
	s_waitcnt vmcnt(0)
	s_barrier
	s_mov_b64 s[4:5], exec
	v_readlane_b32 s6, v253, 30
	v_readlane_b32 s7, v253, 31
	v_readlane_b32 s92, v253, 51
	s_and_b64 s[6:7], s[4:5], s[6:7]
	v_readlane_b32 s93, v253, 52
	v_readlane_b32 s12, v252, 23
	s_mov_b64 exec, s[6:7]
	s_cbranch_execz .LBB0_868
	s_lshl_b32 s8, s58, 6
	s_ashr_i32 s9, s8, 31
	s_lshl_b64 s[8:9], s[8:9], 2
	s_mov_b64 s[6:7], exec
	s_add_u32 s8, s96, s8
	s_addc_u32 s9, s97, s9
	v_mbcnt_lo_u32_b32 v0, s6, 0
	s_add_u32 s10, s8, 0x14000
	v_mbcnt_hi_u32_b32 v0, s7, v0
	s_addc_u32 s11, s9, 0
	v_cmp_eq_u32_e32 vcc, 0, v0
	s_and_saveexec_b64 s[8:9], vcc
	s_cbranch_execz .LBB0_837
	s_bcnt1_i32_b64 s6, s[6:7]
	v_mov_b32_e32 v1, 0
	v_mov_b32_e32 v2, s6
	global_atomic_add v1, v1, v2, s[10:11] sc0

.LBB0_852:
	s_or_b64 exec, exec, s[8:9]
	v_mov_b32_e32 v0, v254
	s_waitcnt vmcnt(0)
	v_cmp_lt_u32_e32 vcc, 63, v0
	s_cbranch_vccnz .LBB0_867
	v_add_u32_e32 v0, 1, v1
	s_mov_b64 s[8:9], 0
	v_mov_b32_e32 v1, 0
	s_branch .LBB0_855

.LBB0_908:
	v_readlane_b32 s98, v253, 30
	v_readlane_b32 s99, v253, 31
	s_mov_b64 s[100:101], exec
	s_and_b64 exec, exec, s[98:99]
	s_cbranch_execz .Lfp3_skip
	v_mov_b32_e32 v254, 0
	global_load_dword v254, v254, s[96:97] offset:512 sc1
.Lfp3_skip:
	s_mov_b64 exec, s[100:101]
	s_waitcnt vmcnt(0)
	s_mov_b64 s[10:11], -1
	s_waitcnt vmcnt(0) lgkmcnt(0)
	s_barrier
	s_mov_b64 s[6:7], exec
	v_readlane_b32 s8, v253, 30
	v_readlane_b32 s9, v253, 31
	s_and_b64 s[8:9], s[6:7], s[8:9]
	s_mov_b64 exec, s[8:9]
	s_cbranch_execz .LBB0_912
	s_mov_b64 s[10:11], exec
	v_mbcnt_lo_u32_b32 v0, s10, 0
	v_mbcnt_hi_u32_b32 v0, s11, v0
	v_cmp_eq_u32_e32 vcc, 0, v0
	s_and_saveexec_b64 s[8:9], vcc
	s_cbranch_execz .LBB0_911
	s_lshl_b32 s18, s58, 6
	s_ashr_i32 s19, s18, 31
	s_lshl_b64 s[18:19], s[18:19], 2
	s_add_u32 s18, s96, s18
	s_addc_u32 s19, s97, s19
	s_bcnt1_i32_b64 s10, s[10:11]
	v_mov_b32_e32 v1, 0x14000
	v_mov_b32_e32 v2, s10
	global_atomic_add v1, v1, v2, s[18:19] sc0

.LBB0_934:
	s_or_b64 exec, exec, s[18:19]
	v_mov_b32_e32 v0, v254
	s_waitcnt vmcnt(0)
	v_cmp_lt_u32_e32 vcc, 31, v0
	s_cbranch_vccnz .LBB0_949
	v_add_u32_e32 v0, 1, v1
	s_mov_b64 s[10:11], 0
	v_mov_b32_e32 v1, 0
	s_branch .LBB0_937

.LBB0_1194:
	v_readlane_b32 s98, v253, 30
	v_readlane_b32 s99, v253, 31
	s_mov_b64 s[100:101], exec
	s_and_b64 exec, exec, s[98:99]
	s_cbranch_execz .Lfp4_skip
	v_mov_b32_e32 v254, 0
	global_load_dword v254, v254, s[96:97] offset:1280 sc1
.Lfp4_skip:
	s_mov_b64 exec, s[100:101]
	s_waitcnt vmcnt(0)
	s_waitcnt vmcnt(0)
	s_barrier
	s_mov_b64 s[0:1], exec
	v_readlane_b32 s6, v253, 30
	v_readlane_b32 s7, v253, 31
	s_and_b64 s[6:7], s[0:1], s[6:7]
	s_mov_b64 exec, s[6:7]
	s_cbranch_execz .LBB0_1228
	s_lshl_b32 s8, s58, 6
	s_ashr_i32 s9, s8, 31
	s_lshl_b64 s[8:9], s[8:9], 2
	s_mov_b64 s[6:7], exec
	s_add_u32 s8, s96, s8
	s_addc_u32 s9, s97, s9
	v_mbcnt_lo_u32_b32 v0, s6, 0
	s_add_u32 s10, s8, 0x14000
	v_mbcnt_hi_u32_b32 v0, s7, v0
	s_addc_u32 s11, s9, 0
	v_cmp_eq_u32_e32 vcc, 0, v0
	s_and_saveexec_b64 s[8:9], vcc
	s_cbranch_execz .LBB0_1197
	s_bcnt1_i32_b64 s6, s[6:7]
	v_mov_b32_e32 v1, 0
	v_mov_b32_e32 v2, s6
	global_atomic_add v1, v1, v2, s[10:11] sc0

.LBB0_1212:
	s_or_b64 exec, exec, s[8:9]
	v_mov_b32_e32 v0, v254
	s_waitcnt vmcnt(0)
	v_cmp_le_u32_e32 vcc, s23, v0
	s_cbranch_vccnz .LBB0_1227
	v_add_u32_e32 v0, 1, v1
	s_mov_b64 s[8:9], 0
	v_mov_b32_e32 v1, 0
	s_mov_b32 s22, 0x40001
	s_branch .LBB0_1215
